# P0 lora-weight gather/convert loop de-serialised: 9 items per thread branch-free, all loads issued before the first wait (was 9 dependent load-wait-store rounds); on top of the P12 rewrite
# speedup vs baseline: 1.0044x; 1.0028x over previous
; __device__ __forceinline__ unsigned f2bf(float f) { unsigned u = __float_as_uint(f); return (u + 0x7fffu + ((u >> 16) & 1u)) >> 16; }
; __device__ __forceinline__ void phase_prologue(const Params& p, LAS unsigned char* lds) {
;     ...
;     { bf16* WL = (bf16*)(ws + WS_W_LORA); const int gt = blockIdx.x * NTHR + tid, NGT = G * NTHR;
;       for (int i = gt; i < N_LORA * K_LORA; i += NGT) { const int n = i / K_LORA, k = i % K_LORA; float v = 0.f;
;           if (n < 1024) { if (k < 64) v = p.in[I_W2][k * 1024 + n]; }
;           else if (n < 2048) { if (k >= 64 && k < 128) v = p.in[I_A2][(k - 64) * 1024 + (n - 1024)]; }
;           else { if (k >= 128 && k < 288) v = p.in[I_G2][(k - 128) * 1024 + (n - 2048)]; }
;           WL[i] = (bf16)f2bf(v); } }
.LBB0_288:
	s_or_b64 exec, exec, s[0:1]
	v_add_u32_e32 v2, s33, v144
	s_mov_b32 s0, 0x120000
	v_cmp_gt_i32_e32 vcc, s0, v2
	s_and_saveexec_b64 s[0:1], vcc
	s_cbranch_execz .LBB0_305
	v_readlane_b32 s44, v244, 22
	v_readlane_b32 s45, v244, 23
	s_add_u32 s4, s28, 0x2600000
	s_addc_u32 s5, s29, 0
	s_movk_i32 s33, 0xa0
	s_movk_i32 s40, 0x7fff
	v_mov_b32_e32 v3, v2
	v_lshrrev_b32_e32 v4, 7, v3
	v_mul_u32_u24_e32 v4, 0xaaab, v4
	v_lshrrev_b32_e32 v4, 17, v4
	v_mul_u32_u24_e32 v5, 0x180, v4
	v_sub_u32_e32 v5, v3, v5
	v_cmp_gt_u32_e64 s[10:11], 64, v5
	v_lshl_add_u32 v6, v5, 10, v4
	v_lshlrev_b32_e32 v6, 2, v6
	s_nop 0
	v_cndmask_b32_e64 v131, 0, v6, s[10:11]
	s_nop 0
	global_load_dword v131, v131, s[78:79]
	v_add_u32_e32 v3, 0x20000, v2
	v_lshrrev_b32_e32 v4, 7, v3
	v_mul_u32_u24_e32 v4, 0xaaab, v4
	v_lshrrev_b32_e32 v4, 17, v4
	v_mul_u32_u24_e32 v5, 0x180, v4
	v_sub_u32_e32 v5, v3, v5
	v_cmp_gt_u32_e64 s[12:13], 64, v5
	v_lshl_add_u32 v6, v5, 10, v4
	v_lshlrev_b32_e32 v6, 2, v6
	s_nop 0
	v_cndmask_b32_e64 v132, 0, v6, s[12:13]
	s_nop 0
	global_load_dword v132, v132, s[78:79]
	v_add_u32_e32 v3, 0x40000, v2
	v_lshrrev_b32_e32 v4, 7, v3
	v_mul_u32_u24_e32 v4, 0xaaab, v4
	v_lshrrev_b32_e32 v4, 17, v4
	v_mul_u32_u24_e32 v5, 0x180, v4
	v_sub_u32_e32 v5, v3, v5
	v_cmp_gt_u32_e64 s[14:15], 64, v5
	v_lshl_add_u32 v6, v5, 10, v4
	v_lshlrev_b32_e32 v6, 2, v6
	s_nop 0
	v_cndmask_b32_e64 v133, 0, v6, s[14:15]
	s_nop 0
	global_load_dword v133, v133, s[78:79]
	v_add_u32_e32 v3, 0x60000, v2
	v_lshrrev_b32_e32 v4, 7, v3
	v_mul_u32_u24_e32 v4, 0xaaab, v4
	v_lshrrev_b32_e32 v4, 17, v4
	v_mul_u32_u24_e32 v5, 0x180, v4
	v_sub_u32_e32 v5, v3, v5
	v_add_u32_e32 v5, 0xffffffc0, v5
	v_cmp_gt_u32_e64 s[16:17], 64, v5
	v_lshl_add_u32 v6, v5, 10, v4
	v_add_u32_e32 v6, 0xfffffc00, v6
	v_lshlrev_b32_e32 v6, 2, v6
	s_nop 0
	v_cndmask_b32_e64 v134, 0, v6, s[16:17]
	s_nop 0
	global_load_dword v134, v134, s[82:83]
	v_add_u32_e32 v3, 0x80000, v2
	v_lshrrev_b32_e32 v4, 7, v3
	v_mul_u32_u24_e32 v4, 0xaaab, v4
	v_lshrrev_b32_e32 v4, 17, v4
	v_mul_u32_u24_e32 v5, 0x180, v4
	v_sub_u32_e32 v5, v3, v5
	v_add_u32_e32 v5, 0xffffffc0, v5
	v_cmp_gt_u32_e64 s[18:19], 64, v5
	v_lshl_add_u32 v6, v5, 10, v4
	v_add_u32_e32 v6, 0xfffffc00, v6
	v_lshlrev_b32_e32 v6, 2, v6
	s_nop 0
	v_cndmask_b32_e64 v135, 0, v6, s[18:19]
	s_nop 0
	global_load_dword v135, v135, s[82:83]
	v_add_u32_e32 v3, 0xa0000, v2
	v_lshrrev_b32_e32 v4, 7, v3
	v_mul_u32_u24_e32 v4, 0xaaab, v4
	v_lshrrev_b32_e32 v4, 17, v4
	v_mul_u32_u24_e32 v5, 0x180, v4
	v_sub_u32_e32 v5, v3, v5
	v_add_u32_e32 v5, 0xffffffc0, v5
	v_cmp_gt_u32_e64 s[36:37], 64, v5
	v_lshl_add_u32 v6, v5, 10, v4
	v_add_u32_e32 v6, 0xfffffc00, v6
	v_lshlrev_b32_e32 v6, 2, v6
	s_nop 0
	v_cndmask_b32_e64 v136, 0, v6, s[36:37]
	s_nop 0
	global_load_dword v136, v136, s[82:83]
	v_add_u32_e32 v3, 0xc0000, v2
	v_lshrrev_b32_e32 v4, 7, v3
	v_mul_u32_u24_e32 v4, 0xaaab, v4
	v_lshrrev_b32_e32 v4, 17, v4
	v_mul_u32_u24_e32 v5, 0x180, v4
	v_sub_u32_e32 v5, v3, v5
	v_add_u32_e32 v5, 0xffffff80, v5
	v_cmp_gt_u32_e64 s[38:39], s33, v5
	v_lshl_add_u32 v6, v5, 10, v4
	v_add_u32_e32 v6, 0xfffff800, v6
	v_lshlrev_b32_e32 v6, 2, v6
	s_nop 0
	v_cndmask_b32_e64 v137, 0, v6, s[38:39]
	s_nop 0
	global_load_dword v137, v137, s[44:45]
	v_add_u32_e32 v3, 0xe0000, v2
	v_lshrrev_b32_e32 v4, 7, v3
	v_mul_u32_u24_e32 v4, 0xaaab, v4
	v_lshrrev_b32_e32 v4, 17, v4
	v_mul_u32_u24_e32 v5, 0x180, v4
	v_sub_u32_e32 v5, v3, v5
	v_add_u32_e32 v5, 0xffffff80, v5
	v_cmp_gt_u32_e64 s[46:47], s33, v5
	v_lshl_add_u32 v6, v5, 10, v4
	v_add_u32_e32 v6, 0xfffff800, v6
	v_lshlrev_b32_e32 v6, 2, v6
	s_nop 0
	v_cndmask_b32_e64 v138, 0, v6, s[46:47]
	s_nop 0
	global_load_dword v138, v138, s[44:45]
	v_add_u32_e32 v3, 0x100000, v2
	v_lshrrev_b32_e32 v4, 7, v3
	v_mul_u32_u24_e32 v4, 0xaaab, v4
	v_lshrrev_b32_e32 v4, 17, v4
	v_mul_u32_u24_e32 v5, 0x180, v4
	v_sub_u32_e32 v5, v3, v5
	v_add_u32_e32 v5, 0xffffff80, v5
	v_cmp_gt_u32_e64 s[48:49], s33, v5
	v_lshl_add_u32 v6, v5, 10, v4
	v_add_u32_e32 v6, 0xfffff800, v6
	v_lshlrev_b32_e32 v6, 2, v6
	s_nop 0
	v_cndmask_b32_e64 v139, 0, v6, s[48:49]
	s_nop 0
	global_load_dword v139, v139, s[44:45]
	s_waitcnt vmcnt(8)
	v_cndmask_b32_e64 v3, 0, v131, s[10:11]
	v_mov_b32_e32 v5, v2
	v_bfe_u32 v4, v3, 16, 1
	v_lshlrev_b32_e32 v5, 1, v5
	v_add3_u32 v3, v3, v4, s40
	s_nop 0
	global_store_short_d16_hi v5, v3, s[4:5]
	s_waitcnt vmcnt(8)
	v_cndmask_b32_e64 v3, 0, v132, s[12:13]
	v_add_u32_e32 v5, 0x20000, v2
	v_bfe_u32 v4, v3, 16, 1
	v_lshlrev_b32_e32 v5, 1, v5
	v_add3_u32 v3, v3, v4, s40
	s_nop 0
	global_store_short_d16_hi v5, v3, s[4:5]
	s_waitcnt vmcnt(8)
	v_cndmask_b32_e64 v3, 0, v133, s[14:15]
	v_add_u32_e32 v5, 0x40000, v2
	v_bfe_u32 v4, v3, 16, 1
	v_lshlrev_b32_e32 v5, 1, v5
	v_add3_u32 v3, v3, v4, s40
	s_nop 0
	global_store_short_d16_hi v5, v3, s[4:5]
	s_waitcnt vmcnt(8)
	v_cndmask_b32_e64 v3, 0, v134, s[16:17]
	v_add_u32_e32 v5, 0x60000, v2
	v_bfe_u32 v4, v3, 16, 1
	v_lshlrev_b32_e32 v5, 1, v5
	v_add3_u32 v3, v3, v4, s40
	s_nop 0
	global_store_short_d16_hi v5, v3, s[4:5]
	s_waitcnt vmcnt(8)
	v_cndmask_b32_e64 v3, 0, v135, s[18:19]
	v_add_u32_e32 v5, 0x80000, v2
	v_bfe_u32 v4, v3, 16, 1
	v_lshlrev_b32_e32 v5, 1, v5
	v_add3_u32 v3, v3, v4, s40
	s_nop 0
	global_store_short_d16_hi v5, v3, s[4:5]
	s_waitcnt vmcnt(8)
	v_cndmask_b32_e64 v3, 0, v136, s[36:37]
	v_add_u32_e32 v5, 0xa0000, v2
	v_bfe_u32 v4, v3, 16, 1
	v_lshlrev_b32_e32 v5, 1, v5
	v_add3_u32 v3, v3, v4, s40
	s_nop 0
	global_store_short_d16_hi v5, v3, s[4:5]
	s_waitcnt vmcnt(8)
	v_cndmask_b32_e64 v3, 0, v137, s[38:39]
	v_add_u32_e32 v5, 0xc0000, v2
	v_bfe_u32 v4, v3, 16, 1
	v_lshlrev_b32_e32 v5, 1, v5
	v_add3_u32 v3, v3, v4, s40
	s_nop 0
	global_store_short_d16_hi v5, v3, s[4:5]
	s_waitcnt vmcnt(8)
	v_cndmask_b32_e64 v3, 0, v138, s[46:47]
	v_add_u32_e32 v5, 0xe0000, v2
	v_bfe_u32 v4, v3, 16, 1
	v_lshlrev_b32_e32 v5, 1, v5
	v_add3_u32 v3, v3, v4, s40
	s_nop 0
	global_store_short_d16_hi v5, v3, s[4:5]
	s_waitcnt vmcnt(8)
	v_cndmask_b32_e64 v3, 0, v139, s[48:49]
	v_add_u32_e32 v5, 0x100000, v2
	v_bfe_u32 v4, v3, 16, 1
	v_lshlrev_b32_e32 v5, 1, v5
	v_add3_u32 v3, v3, v4, s40
	s_nop 0
	global_store_short_d16_hi v5, v3, s[4:5]
